# diff unit loop: redundant second queue-slot barrier dropped; row-norm phases use DPP wave reductions
# baseline (speedup 1.0000x reference)
; #define ATT_LSTORE(buf) do { LAS unsigned char* b_ = lds + (buf) * BUF; \
;         _Pragma("unroll") for (int i = 0; i < KPT; ++i) { if (KCH % NTHREADS == 0 || tid + i * NTHREADS < KCH) *(LAS u32x4*)(b_ + klo[i]) = kreg[i]; } \
;         _Pragma("unroll") for (int i = 0; i < VPT; ++i) *(LAS u32x4*)(b_ + vlo[i]) = vreg[i]; } while (0)
; template <int DQK, int DV, int FLAGS, int qp, int kp, int vts, int op> ...
;     ...
;     u32x4 kreg[KPT], vreg[VPT];
;     unsigned kgo[KPT], vgo[VPT], klo[KPT], vlo[VPT];
; #pragma unroll
;     for (int i = 0; i < KPT; ++i) { const int c = tid + i * NTHREADS; const int row = c / KC, cc = c % KC; kgo[i] = (unsigned)(row * kp + cc * 8) * 2u; klo[i] = (unsigned)(row * KROW + cc * 16); }
; #pragma unroll
;     for (int i = 0; i < VPT; ++i) { const int c = tid + i * NTHREADS; const int d = c >> 3, cc = c & 7; vgo[i] = (unsigned)(d * vts + cc * 8) * 2u; vlo[i] = (unsigned)(KT_BYTES + d * VROW + cc * 16); }
;     ...
;     ATT_GLOAD((FLAGS & AF_REV) ? kt_hi - 1 : kt_lo); ATT_LSTORE(0);
;     __syncthreads();
; __global__ void __launch_bounds__(NTHREADS, 2) mega_fwd(Args args) {
;     ...
;                 for (;;) {
;                     if (threadIdx.x == 0) *qslot = __hip_atomic_fetch_add(qctr, 1u, __ATOMIC_RELAXED, __HIP_MEMORY_SCOPE_AGENT);
;                     __syncthreads();
;                     const int j = (int)*qslot;
;                     __syncthreads();
;                     if (j >= 2048) break;
;                     const int qb = 63 - (j >> 5), c = j & 31, h = 7 - (c >> 2), b = (c >> 1) & 1, st = c & 1; const size_t row0 = (size_t)b * SEQ + qb * 256;
;                     const float slope2 = exp2f(-(float)(h + 1)) * LOG2E;
;                     const int q0 = qb * 256, cutkeys = (int)((2.0f * Bq + 152.0f) / slope2) + 1;
;                     const int klo = (q0 - 63 - cutkeys >= 0) ? (q0 - 63 - cutkeys) / 64 + 1 : 0;
.LBB0_930:
	s_or_b64 exec, exec, s[6:7]
	v_mov_b32_e32 v0, s12
	s_waitcnt lgkmcnt(0)
	s_barrier
	ds_read_b32 v0, v0
	s_movk_i32 s3, 0x7ff
	s_mov_b64 s[6:7], -1
	s_waitcnt lgkmcnt(0)
	v_cmp_lt_i32_e32 vcc, s3, v0
	v_readfirstlane_b32 s2, v0
	s_cbranch_vccnz .LBB0_925
	s_bfe_u32 s5, s2, 0x30002
	s_ashr_i32 s11, s2, 5
	s_bfe_u32 s6, s2, 0x10001
	s_and_b32 s4, s2, 1
	s_sub_i32 s2, 8, s5
	v_cvt_f32_ubyte0_e32 v0, s2
	s_mov_b32 s2, 0x42fc0000
	v_cmp_lt_f32_e32 vcc, s2, v0
	s_lshl_b32 s10, s11, 8
	v_readlane_b32 s34, v255, 39
	v_cndmask_b32_e32 v2, 0, v219, vcc
	v_sub_f32_e32 v0, v2, v0
	v_exp_f32_e32 v0, v0
	s_sub_i32 s34, 0x3f00, s10
	s_and_b64 s[2:3], vcc, exec
	s_cselect_b32 s2, 0xffffffc0, 0
	v_ldexp_f32 v0, v0, s2
	v_mul_f32_e32 v14, 0x3fb8aa3b, v0
	v_div_scale_f32 v0, s[2:3], v14, v14, v221
	v_rcp_f32_e32 v2, v0
	v_readlane_b32 s35, v255, 40
	v_readlane_b32 s20, v252, 0
	v_readlane_b32 s21, v252, 1
	v_fma_f32 v3, -v0, v2, 1.0
	v_fmac_f32_e32 v2, v3, v2
	v_div_scale_f32 v3, vcc, v221, v14, v221
	v_mul_f32_e32 v4, v3, v2
	v_fma_f32 v5, -v0, v4, v3
	v_fmac_f32_e32 v4, v5, v2
	v_fma_f32 v0, -v0, v4, v3
	v_div_fmas_f32 v0, v0, v2, v4
	v_div_fixup_f32 v0, v0, v14, v221
	v_cvt_i32_f32_e32 v0, v0
	v_readlane_b32 s18, v252, 24
	v_readlane_b32 s19, v252, 25
	v_mov_b32_e32 v15, v212
	v_readfirstlane_b32 s2, v0
	s_not_b32 s2, s2
	s_sub_i32 s2, s2, s10
	s_addk_i32 s2, 0x3ec1
	s_lshr_b32 s3, s2, 6
	s_not_b32 s3, s3
	s_cmp_gt_i32 s2, -1
	s_cselect_b32 s14, s3, 0
	s_lshl_b32 s7, s6, 24
	s_lshl_b64 s[2:3], s[34:35], 10
	s_add_u32 s2, s2, s7
	s_addc_u32 s3, s3, 0
	s_lshl_b64 s[30:31], s[2:3], 1
	s_add_u32 s2, s20, s30
	s_addc_u32 s3, s21, s31
	s_lshl_b32 s5, s5, 7
	s_xor_b32 s12, s5, 0x380
	s_lshl_b32 s7, s4, 7
	s_lshl_b32 s5, s12, 1
	s_or_b32 s7, s7, s5
	s_add_u32 s8, s2, s7
	s_addc_u32 s9, s3, 0
	s_lshl_b32 s2, s6, 25
	v_readlane_b32 s3, v253, 7
	s_add_u32 s3, s3, s2
	v_readlane_b32 s6, v253, 8
	s_addc_u32 s13, s6, 0
	s_add_u32 s6, s3, s7
	s_addc_u32 s7, s13, 0
	s_add_u32 s2, s18, s2
	s_addc_u32 s3, s19, 0
	s_lshl_b32 s12, s12, 15
	s_add_u32 s18, s2, s12
	s_addc_u32 s19, s3, 0
	v_readfirstlane_b32 s2, v15
	s_ashr_i32 s2, s2, 1
	s_movk_i32 s3, 0xffe0
	v_mov_b32_e32 v0, s2
	v_bfi_b32 v176, s3, v0, v15
	v_ashrrev_i32_e32 v177, 31, v176
	v_ashrrev_i32_e32 v0, 31, v15
	s_lshl_b32 s11, s11, 2
	v_lshlrev_b64 v[2:3], 11, v[176:177]
	v_lshrrev_b32_e32 v0, 29, v0
	v_lshl_add_u64 v[2:3], s[8:9], 0, v[2:3]
	v_add_u32_e32 v0, v15, v0
	s_sub_i32 s8, 0xff, s11
	v_writelane_b32 v255, s34, 39
	s_mov_b32 s9, s35
	v_ashrrev_i32_e32 v21, 3, v0
	v_and_b32_e32 v0, 0xffffff8, v0
	s_lshl_b64 s[12:13], s[8:9], 17
	v_bfe_u32 v17, v15, 5, 1
	v_sub_u32_e32 v4, v15, v0
	s_add_u32 s12, s6, s12
	v_lshlrev_b32_e32 v194, 4, v17
	v_mov_b32_e32 v195, v1
	v_lshlrev_b32_e32 v0, 4, v15
	v_add_u32_e32 v5, 0x200, v15
	v_lshlrev_b32_e32 v4, 4, v4
	s_addc_u32 s13, s7, s13
	s_lshl_b64 s[8:9], s[8:9], 7
	v_and_b32_e32 v20, 0x70, v0
	v_ashrrev_i32_e32 v22, 3, v15
	v_ashrrev_i32_e32 v23, 3, v5
	v_lshl_add_u32 v16, v21, 11, v4
	s_add_u32 s8, s18, s8
	v_lshl_add_u64 v[18:19], v[2:3], 0, v[194:195]
	v_lshl_or_b32 v0, v22, 15, v20
	v_lshl_or_b32 v196, v23, 15, v20
	s_addc_u32 s9, s19, s9
	global_load_dwordx4 v[148:151], v16, s[12:13]
	global_load_dwordx4 v[152:155], v0, s[8:9]
	global_load_dwordx4 v[156:159], v196, s[8:9]
	s_sub_u32 s98, s12, 0x20000
	s_subb_u32 s99, s13, 0
	global_load_dwordx4 v[224:227], v16, s[98:99]
	s_sub_u32 s98, s8, 0x80
	s_subb_u32 s99, s9, 0
	global_load_dwordx4 v[228:231], v0, s[98:99]
	global_load_dwordx4 v[232:235], v196, s[98:99]
	global_load_dwordx4 v[2:5], v[18:19], off
	global_load_dwordx4 v[6:9], v[18:19], off offset:32
	global_load_dwordx4 v[10:13], v[18:19], off offset:64
	global_load_dwordx4 v[144:147], v[18:19], off offset:96
	s_movk_i32 s3, 0x90
	v_and_b32_e32 v18, 63, v15
	v_mad_u64_u32 v[200:201], s[12:13], v22, s3, v[20:21]
	v_mad_u64_u32 v[202:203], s[12:13], v23, s3, v[20:21]
	s_movk_i32 s3, 0xf890
	v_lshlrev_b32_e32 v18, 2, v18
	v_mad_u64_u32 v[204:205], s[12:13], v21, s3, v[16:17]
	s_sub_i32 s3, s14, s11
	v_writelane_b32 v255, s35, 40
	s_mov_b64 s[8:9], -1
	v_add_u32_e32 v21, 0, v204
	s_cmpk_gt_i32 s3, 0xff00
	v_xor_b32_e32 v195, 0x80, v18
	v_readlane_b32 s22, v252, 2
	v_readlane_b32 s23, v252, 3
	v_add_u32_e32 v19, 0, v200
	v_add_u32_e32 v20, 0, v202
	s_waitcnt vmcnt(9)
	ds_write_b128 v21, v[148:151]
	s_waitcnt vmcnt(8)
	ds_write_b128 v19, v[152:155] offset:9216
	s_waitcnt vmcnt(7)
	ds_write_b128 v20, v[156:159] offset:9216
	s_waitcnt lgkmcnt(0)
	s_barrier
	s_cbranch_scc1 .LBB0_933
	v_xor_b32_e32 v80, 0x80, v18
	s_mov_b64 s[8:9], 0
